# GLA sequential pass: wait for chunk loads where they are used (one step later), so each load has two steps to land; odd-step v fragment via v248-255
# speedup vs baseline: 1.0025x; 1.0025x over previous
.LBB0_668:
	s_or_b64 exec, exec, s[16:17]
	s_add_u32 s16, s40, 0x35758f00
	s_addc_u32 s17, s41, 0
	s_lshl_b64 s[26:27], s[26:27], 8
	v_lshl_add_u64 v[16:17], s[26:27], 0, v[24:25]
	v_or_b32_e32 v16, v16, v124
	s_waitcnt vmcnt(0)
	v_mov_b32_e32 v130, v101
	v_lshlrev_b64 v[16:17], 7, v[16:17]
	v_mov_b32_e32 v101, 0
	v_lshl_add_u64 v[16:17], s[24:25], 0, v[16:17]
	v_lshlrev_b32_e32 v30, 1, v28
	v_mov_b32_e32 v31, v101
	v_lshl_add_u64 v[32:33], v[16:17], 0, v[30:31]
	global_load_dwordx4 v[248:251], v[32:33], off
	global_load_dwordx4 v[252:255], v[32:33], off offset:64
	s_add_u32 s22, s22, s18
	s_addc_u32 s23, s23, 0
	s_lshl_b32 s6, s6, 5
	s_lshl_b32 s7, s28, 3
	v_mov_b32_e32 v27, v101
	s_or_b32 s6, s7, s6
	v_lshl_add_u64 v[108:109], s[22:23], 0, v[26:27]
	s_ashr_i32 s7, s6, 31
	v_lshlrev_b32_e32 v26, 2, v156
	s_lshl_b32 s18, s28, 10
	v_lshl_add_u64 v[114:115], s[20:21], 0, v[26:27]
	s_add_u32 s20, s16, s18
	s_addc_u32 s21, s17, 0
	v_lshlrev_b32_e32 v110, 2, v24
	v_mov_b32_e32 v111, v101
	v_or_b32_e32 v112, v24, v124
	v_lshl_add_u64 v[24:25], s[20:21], 0, v[110:111]
	v_mov_b32_e32 v107, v101
	v_add_u32_e32 v29, 0, v28
	s_movk_i32 s13, 0x110
	v_lshl_add_u64 v[116:117], v[24:25], 0, v[106:107]
	v_mov_b32_e32 v24, 0x3300
	v_mad_u32_u24 v129, v124, s13, v29
	v_mad_u32_u24 v27, v124, s13, v24
	s_movk_i32 s13, 0x90
	v_mad_u32_u24 v32, v124, s13, 0
	s_add_i32 s13, 0, 0x11a00
	s_lshl_b64 s[6:7], s[6:7], 2
	s_add_u32 s6, s40, s6
	v_lshlrev_b32_e32 v24, 7, v112
	v_mov_b32_e32 v25, v101
	s_addc_u32 s7, s41, s7
	v_lshlrev_b32_e32 v28, 2, v113
	v_or_b32_e32 v33, 64, v106
	v_or_b32_e32 v34, 0x80, v106
	v_or_b32_e32 v35, 0xc0, v106
	v_or_b32_e32 v36, 0x100, v106
	v_or_b32_e32 v37, 0x140, v106
	v_or_b32_e32 v38, 0x180, v106
	v_or_b32_e32 v39, 0x1c0, v106
	v_lshl_add_u64 v[24:25], s[24:25], 0, v[24:25]
	s_add_u32 s20, s6, 0x6330d00
	v_add_u32_e32 v107, s13, v26
	v_add_u32_e32 v131, 0, v26
	s_addc_u32 s21, s7, 0
	v_lshl_add_u64 v[118:119], s[24:25], 0, v[30:31]
	v_lshl_add_u64 v[120:121], v[24:25], 0, v[30:31]
	v_lshlrev_b32_e32 v122, 2, v28
	s_mov_b32 s31, 0x10000
	s_mov_b32 s33, 0x20000
	s_mov_b32 s34, 0x30000
	v_add_u32_e32 v132, v29, v27
	v_add_u32_e32 v133, v32, v106
	v_add_u32_e32 v135, s13, v33
	v_add_u32_e32 v136, s13, v34
	v_add_u32_e32 v137, s13, v35
	v_add_u32_e32 v138, s13, v36
	v_add_u32_e32 v139, s13, v37
	v_add_u32_e32 v140, s13, v38
	v_add_u32_e32 v141, s13, v39
	s_mov_b32 s35, 0
	v_mov_b32_e32 v56, v101
	v_mov_b32_e32 v57, v101
	v_mov_b32_e32 v58, v101
	v_mov_b32_e32 v59, v101
	v_mov_b32_e32 v60, v101
	v_mov_b32_e32 v61, v101
	v_mov_b32_e32 v62, v101
	v_mov_b32_e32 v63, v101
	v_mov_b32_e32 v64, v101
	v_mov_b32_e32 v65, v101
	v_mov_b32_e32 v66, v101
	v_mov_b32_e32 v67, v101
	v_mov_b32_e32 v68, v101
	v_mov_b32_e32 v69, v101
	v_mov_b32_e32 v70, v101
	v_mov_b32_e32 v71, v101
	v_mov_b32_e32 v72, v101
	v_mov_b32_e32 v73, v101
	v_mov_b32_e32 v74, v101
	v_mov_b32_e32 v75, v101
	v_mov_b32_e32 v76, v101
	v_mov_b32_e32 v77, v101
	v_mov_b32_e32 v78, v101
	v_mov_b32_e32 v79, v101
	v_mov_b32_e32 v80, v101
	v_mov_b32_e32 v81, v101
	v_mov_b32_e32 v82, v101
	v_mov_b32_e32 v83, v101
	v_mov_b32_e32 v84, v101
	v_mov_b32_e32 v85, v101
	v_mov_b32_e32 v86, v101
	v_mov_b32_e32 v87, v101
	s_branch .LBB0_671

.LBB0_670:
	v_mov_b64_e32 v[54:55], v[22:23]
	v_mov_b64_e32 v[52:53], v[20:21]
	s_andn2_b64 vcc, exec, s[22:23]
	s_mov_b32 s35, s18
	s_waitcnt lgkmcnt(0)
	s_barrier
	s_cbranch_vccz .LBB0_699

.LBB0_690:
	v_add_u32_e32 v111, 0x4800, v129
	v_cvt_pk_bf16_f32 v88, v84, v85
	v_cvt_pk_bf16_f32 v89, v86, v87
	v_cvt_pk_bf16_f32 v90, v80, v81
	v_cvt_pk_bf16_f32 v91, v82, v83
	ds_read2_b64 v[144:147], v111 offset1:4
	v_cvt_pk_bf16_f32 v92, v76, v77
	v_cvt_pk_bf16_f32 v93, v78, v79
	v_cvt_pk_bf16_f32 v94, v72, v73
	v_cvt_pk_bf16_f32 v95, v74, v75
	ds_read2_b64 v[152:155], v111 offset0:8 offset1:12
	s_waitcnt lgkmcnt(1)
	v_mfma_f32_16x16x32_bf16 v[144:147], v[88:91], v[144:147], 0
	v_cvt_pk_bf16_f32 v148, v68, v69
	v_cvt_pk_bf16_f32 v149, v70, v71
	v_cvt_pk_bf16_f32 v150, v64, v65
	v_cvt_pk_bf16_f32 v151, v66, v67
	ds_read2_b64 v[162:165], v111 offset0:16 offset1:20
	s_waitcnt lgkmcnt(1)
	v_mfma_f32_16x16x32_bf16 v[144:147], v[92:95], v[152:155], v[144:147]
	v_cvt_pk_bf16_f32 v158, v60, v61
	v_cvt_pk_bf16_f32 v159, v62, v63
	v_cvt_pk_bf16_f32 v160, v56, v57
	v_cvt_pk_bf16_f32 v161, v58, v59
	ds_read2_b64 v[152:155], v111 offset0:24 offset1:28
	s_waitcnt lgkmcnt(1)
	v_mfma_f32_16x16x32_bf16 v[144:147], v[148:151], v[162:165], v[144:147]
	v_add_u32_e32 v111, 0x5800, v129
	ds_read2_b64 v[162:165], v111 offset0:40 offset1:44
	v_lshl_or_b32 v123, s35, 6, v124
	s_waitcnt lgkmcnt(1)
	v_mfma_f32_16x16x32_bf16 v[144:147], v[158:161], v[152:155], v[144:147]
	ds_read2_b64 v[152:155], v111 offset0:32 offset1:36
	v_or_b32_e32 v174, s10, v123
	v_mov_b32_e32 v175, s11
	s_waitcnt lgkmcnt(0)
	v_mfma_f32_16x16x32_bf16 v[152:155], v[88:91], v[152:155], 0
	v_add_u32_e32 v143, 0, v106
	v_lshlrev_b64 v[178:179], 12, v[174:175]
	v_lshl_add_u64 v[180:181], v[116:117], 0, v[178:179]
	v_mfma_f32_16x16x32_bf16 v[152:155], v[92:95], v[162:165], v[152:155]
	ds_read2_b64 v[162:165], v111 offset0:48 offset1:52
	s_lshl_b32 s24, s12, 2
	s_mov_b32 s25, s19
	s_waitcnt lgkmcnt(0)
	v_mfma_f32_16x16x32_bf16 v[152:155], v[148:151], v[162:165], v[152:155]
	ds_read2_b64 v[162:165], v111 offset0:56 offset1:60
	v_add_u32_e32 v111, 0x6800, v129
	ds_read2_b64 v[166:169], v111 offset0:72 offset1:76
	s_waitcnt lgkmcnt(1)
	v_mfma_f32_16x16x32_bf16 v[152:155], v[158:161], v[162:165], v[152:155]
	ds_read2_b64 v[162:165], v111 offset0:64 offset1:68
	ds_read2_b64 v[170:173], v111 offset0:88 offset1:92
	v_mov_b32_e32 v123, v101
	s_waitcnt lgkmcnt(1)
	v_mfma_f32_16x16x32_bf16 v[162:165], v[88:91], v[162:165], 0
	v_mfma_f32_16x16x32_bf16 v[162:165], v[92:95], v[166:169], v[162:165]
	ds_read2_b64 v[166:169], v111 offset0:80 offset1:84
	v_add_u32_e32 v111, 0x7800, v129
	s_waitcnt lgkmcnt(0)
	v_mfma_f32_16x16x32_bf16 v[162:165], v[148:151], v[166:169], v[162:165]
	ds_read2_b64 v[166:169], v111 offset0:96 offset1:100
	v_mfma_f32_16x16x32_bf16 v[162:165], v[158:161], v[170:173], v[162:165]
	ds_read2_b64 v[170:173], v111 offset0:104 offset1:108
	s_waitcnt lgkmcnt(1)
	v_mfma_f32_16x16x32_bf16 v[88:91], v[88:91], v[166:169], 0
	ds_read2_b64 v[166:169], v111 offset0:112 offset1:116
	ds_read2_b64 v[174:177], v111 offset0:120 offset1:124
	v_mov_b32_e32 v111, v101
	s_waitcnt lgkmcnt(2)
	v_mfma_f32_16x16x32_bf16 v[88:91], v[92:95], v[170:173], v[88:91]
	ds_read_b128 v[92:95], v143 offset:35840
	ds_read_b128 v[170:173], v133
	global_store_dwordx4 v[180:181], v[144:147], off
	s_waitcnt lgkmcnt(1)
	v_pk_mul_f32 v[84:85], v[84:85], v[92:93]
	v_mfma_f32_16x16x32_bf16 v[88:91], v[148:151], v[166:169], v[88:91]
	ds_read_b128 v[144:147], v133 offset:64
	ds_read_b128 v[148:151], v143 offset:35904
	v_pk_mul_f32 v[86:87], v[86:87], v[94:95]
	ds_read_b128 v[92:95], v133 offset:2304
	v_mfma_f32_16x16x32_bf16 v[88:91], v[158:161], v[174:177], v[88:91]
	ds_read_b128 v[158:161], v133 offset:2368
	s_waitcnt lgkmcnt(2)
	v_pk_mul_f32 v[80:81], v[80:81], v[148:149]
	v_pk_mul_f32 v[82:83], v[82:83], v[150:151]
	v_mfma_f32_16x16x32_bf16 v[84:87], v[170:173], v[52:55], v[84:87]
	v_lshl_add_u64 v[170:171], s[16:17], 0, v[178:179]
	v_mfma_f32_16x16x32_bf16 v[84:87], v[144:147], v[48:51], v[84:87]
	ds_read_b128 v[144:147], v143 offset:35968
	ds_read_b128 v[148:151], v133 offset:4608
	s_waitcnt lgkmcnt(1)
	v_pk_mul_f32 v[76:77], v[76:77], v[144:145]
	v_mfma_f32_16x16x32_bf16 v[80:83], v[92:95], v[52:55], v[80:83]
	ds_read_b128 v[92:95], v133 offset:4672
	ds_read_b128 v[166:169], v143 offset:36032
	v_pk_mul_f32 v[78:79], v[78:79], v[146:147]
	ds_read_b128 v[144:147], v133 offset:6912
	v_mfma_f32_16x16x32_bf16 v[80:83], v[158:161], v[48:51], v[80:83]
	ds_read_b128 v[158:161], v133 offset:9280
	s_waitcnt lgkmcnt(2)
	v_pk_mul_f32 v[72:73], v[72:73], v[166:167]
	v_pk_mul_f32 v[74:75], v[74:75], v[168:169]
	v_mfma_f32_16x16x32_bf16 v[76:79], v[148:151], v[52:55], v[76:79]
	ds_read_b128 v[148:151], v133 offset:6976
	s_waitcnt lgkmcnt(2)
	v_mfma_f32_16x16x32_bf16 v[72:75], v[144:147], v[52:55], v[72:75]
	ds_read_b128 v[144:147], v143 offset:36096
	v_mfma_f32_16x16x32_bf16 v[76:79], v[92:95], v[48:51], v[76:79]
	ds_read_b128 v[92:95], v133 offset:9216
	s_waitcnt lgkmcnt(2)
	v_mfma_f32_16x16x32_bf16 v[72:75], v[148:151], v[48:51], v[72:75]
	ds_read_b128 v[148:151], v143 offset:36160
	s_waitcnt lgkmcnt(2)
	v_pk_mul_f32 v[68:69], v[68:69], v[144:145]
	v_pk_mul_f32 v[70:71], v[70:71], v[146:147]
	ds_read_b128 v[144:147], v133 offset:11520
	s_waitcnt lgkmcnt(1)
	v_pk_mul_f32 v[64:65], v[64:65], v[148:149]
	v_mfma_f32_16x16x32_bf16 v[68:71], v[92:95], v[52:55], v[68:71]
	v_lshl_add_u64 v[92:93], v[170:171], 0, s[24:25]
	v_lshl_add_u64 v[92:93], v[92:93], 0, v[110:111]
	v_lshl_add_u64 v[166:167], v[92:93], 0, v[122:123]
	ds_read_b128 v[92:95], v133 offset:11584
	v_pk_mul_f32 v[66:67], v[66:67], v[150:151]
	v_mfma_f32_16x16x32_bf16 v[68:71], v[158:161], v[48:51], v[68:71]
	v_add_co_u32_e32 v158, vcc, s31, v166
	s_waitcnt lgkmcnt(1)
	v_mfma_f32_16x16x32_bf16 v[64:67], v[144:147], v[52:55], v[64:67]
	ds_read_b128 v[144:147], v143 offset:36224
	ds_read_b128 v[148:151], v133 offset:13824
	v_addc_co_u32_e32 v159, vcc, 0, v167, vcc
	global_store_dwordx4 v[158:159], v[152:155], off
	s_waitcnt lgkmcnt(1)
	v_pk_mul_f32 v[60:61], v[60:61], v[144:145]
	ds_read_b128 v[152:155], v133 offset:13888
	v_pk_mul_f32 v[62:63], v[62:63], v[146:147]
	ds_read_b128 v[144:147], v133 offset:16128
	v_mfma_f32_16x16x32_bf16 v[64:67], v[92:95], v[48:51], v[64:67]
	ds_read_b128 v[92:95], v143 offset:36288
	s_waitcnt lgkmcnt(3)
	v_mfma_f32_16x16x32_bf16 v[60:63], v[148:151], v[52:55], v[60:63]
	v_add_co_u32_e32 v148, vcc, s33, v166
	s_nop 1
	v_addc_co_u32_e32 v149, vcc, 0, v167, vcc
	global_store_dwordx4 v[148:149], v[162:165], off
	ds_read_b128 v[148:151], v133 offset:16192
	s_waitcnt lgkmcnt(1)
	v_pk_mul_f32 v[56:57], v[56:57], v[92:93]
	v_pk_mul_f32 v[58:59], v[58:59], v[94:95]
	v_mfma_f32_16x16x32_bf16 v[60:63], v[152:155], v[48:51], v[60:63]
	s_nop 0
	v_mfma_f32_16x16x32_bf16 v[52:55], v[144:147], v[52:55], v[56:59]
	s_waitcnt lgkmcnt(0)
	v_mfma_f32_16x16x32_bf16 v[48:51], v[148:151], v[48:51], v[52:55]
	s_nop 0
	v_add_co_u32_e32 v56, vcc, s34, v166
	s_nop 1
	v_addc_co_u32_e32 v57, vcc, 0, v167, vcc
	global_store_dwordx4 v[56:57], v[88:91], off
	s_sub_u32 s26, s35, 2
	s_cmp_lt_u32 s26, 60
	s_cbranch_scc0 .Lsd_strict
	s_waitcnt vmcnt(14)
	s_branch .Lsd_done
.Lsd_strict:
	s_waitcnt vmcnt(4)
.Lsd_done:
	ds_write_b128 v125, v[0:3] offset:36352
	ds_write_b128 v126, v[4:7] offset:54784
	ds_write_b128 v127, v[8:11] offset:36352
	ds_write_b128 v128, v[12:15] offset:54784
	s_and_saveexec_b64 s[26:27], s[4:5]
	ds_write_b32 v107, v130
	s_or_b64 exec, exec, s[26:27]
	v_mov_b64_e32 v[18:19], v[254:255]
	v_mov_b64_e32 v[22:23], v[250:251]
	s_and_b64 vcc, exec, s[6:7]
	v_mov_b64_e32 v[16:17], v[252:253]
	v_mov_b64_e32 v[20:21], v[248:249]
	s_waitcnt lgkmcnt(0)
	s_barrier
	s_cbranch_vccnz .LBB0_696
	s_add_i32 s26, s35, 3
	s_mov_b32 s27, s19
	s_add_u32 s6, s14, s26
	s_addc_u32 s7, s15, 0
	s_lshl_b64 s[26:27], s[26:27], 6
	s_add_u32 s26, s26, s10
	s_addc_u32 s27, s27, s11
	s_lshl_b64 s[28:29], s[6:7], 14
	s_add_u32 s28, s3, s28
	s_addc_u32 s29, s30, s29
	v_lshl_add_u64 v[0:1], s[28:29], 0, v[98:99]
	v_lshl_add_u64 v[8:9], v[0:1], 0, v[100:101]
	v_mov_b32_e32 v1, s27
	v_or_b32_e32 v0, s26, v97
	v_lshlrev_b64 v[0:1], 10, v[0:1]
	v_lshl_add_u64 v[10:11], v[108:109], 0, v[0:1]
	global_load_dwordx4 v[0:3], v[8:9], off
	global_load_dwordx4 v[4:7], v[10:11], off
	v_lshl_add_u64 v[10:11], s[26:27], 0, v[104:105]
	v_lshl_add_u64 v[8:9], s[28:29], 0, v[102:103]
	v_lshlrev_b64 v[10:11], 10, v[10:11]
	v_lshl_add_u64 v[8:9], v[8:9], 0, v[100:101]
	v_lshl_add_u64 v[12:13], v[108:109], 0, v[10:11]
	global_load_dwordx4 v[8:11], v[8:9], off
	s_nop 0
	global_load_dwordx4 v[12:15], v[12:13], off
	v_mov_b32_e32 v130, 0
	s_and_saveexec_b64 s[26:27], s[4:5]
	s_cbranch_execz .LBB0_695
	s_lshl_b64 s[28:29], s[6:7], 9
	v_lshl_add_u64 v[52:53], v[114:115], 0, s[28:29]
	global_load_dword v130, v[52:53], off
.LBB0_695:
	s_or_b64 exec, exec, s[26:27]
	s_lshl_b64 s[6:7], s[6:7], 15
	v_lshl_add_u64 v[52:53], v[120:121], 0, s[6:7]
	global_load_dwordx4 v[248:251], v[52:53], off
	global_load_dwordx4 v[252:255], v[52:53], off offset:64
.LBB0_696:
	v_add_u32_e32 v111, 0xd000, v129
	v_cvt_pk_bf16_f32 v52, v84, v85
	v_cvt_pk_bf16_f32 v53, v86, v87
	v_cvt_pk_bf16_f32 v54, v80, v81
	v_cvt_pk_bf16_f32 v55, v82, v83
	ds_read2_b64 v[144:147], v111 offset0:192 offset1:196
	v_cvt_pk_bf16_f32 v56, v76, v77
	v_cvt_pk_bf16_f32 v57, v78, v79
	v_cvt_pk_bf16_f32 v58, v72, v73
	v_cvt_pk_bf16_f32 v59, v74, v75
	ds_read2_b64 v[152:155], v111 offset0:200 offset1:204
	s_waitcnt lgkmcnt(1)
	v_mfma_f32_16x16x32_bf16 v[144:147], v[52:55], v[144:147], 0
	v_cvt_pk_bf16_f32 v148, v68, v69
	v_cvt_pk_bf16_f32 v149, v70, v71
	v_cvt_pk_bf16_f32 v150, v64, v65
	v_cvt_pk_bf16_f32 v151, v66, v67
	ds_read2_b64 v[162:165], v111 offset0:208 offset1:212
	s_waitcnt lgkmcnt(1)
	v_mfma_f32_16x16x32_bf16 v[144:147], v[56:59], v[152:155], v[144:147]
	v_cvt_pk_bf16_f32 v158, v60, v61
	v_cvt_pk_bf16_f32 v159, v62, v63
	v_cvt_pk_bf16_f32 v160, v48, v49
	v_cvt_pk_bf16_f32 v161, v50, v51
	ds_read2_b64 v[152:155], v111 offset0:216 offset1:220
	s_waitcnt lgkmcnt(1)
	v_mfma_f32_16x16x32_bf16 v[144:147], v[148:151], v[162:165], v[144:147]
	v_add_u32_e32 v111, 0xe000, v129
	ds_read2_b64 v[162:165], v111 offset0:232 offset1:236
	v_add_u32_e32 v123, 0xd000, v132
	s_waitcnt lgkmcnt(1)
	v_mfma_f32_16x16x32_bf16 v[144:147], v[158:161], v[152:155], v[144:147]
	ds_read2_b64 v[152:155], v111 offset0:224 offset1:228
	s_or_b32 s6, s35, 1
	v_mov_b32_e32 v175, s11
	s_waitcnt lgkmcnt(0)
	v_mfma_f32_16x16x32_bf16 v[152:155], v[52:55], v[152:155], 0
	s_mov_b32 s25, s19
	s_cmp_gt_u32 s6, 62
	v_mfma_f32_16x16x32_bf16 v[152:155], v[56:59], v[162:165], v[152:155]
	ds_read2_b64 v[162:165], v111 offset0:240 offset1:244
	s_waitcnt lgkmcnt(0)
	v_mfma_f32_16x16x32_bf16 v[152:155], v[148:151], v[162:165], v[152:155]
	ds_read2_b64 v[162:165], v111 offset0:248 offset1:252
	v_add_u32_e32 v111, 0xf800, v129
	ds_read2_b64 v[166:169], v111 offset0:8 offset1:12
	s_waitcnt lgkmcnt(1)
	v_mfma_f32_16x16x32_bf16 v[152:155], v[158:161], v[162:165], v[152:155]
	ds_read2_b64 v[162:165], v111 offset1:4
	ds_read2_b64 v[170:173], v111 offset0:24 offset1:28
	s_waitcnt lgkmcnt(1)
	v_mfma_f32_16x16x32_bf16 v[162:165], v[52:55], v[162:165], 0
	v_mfma_f32_16x16x32_bf16 v[162:165], v[56:59], v[166:169], v[162:165]
	ds_read2_b64 v[166:169], v111 offset0:16 offset1:20
	v_lshl_or_b32 v111, s6, 6, v124
	v_or_b32_e32 v174, s10, v111
	s_waitcnt lgkmcnt(0)
	v_mfma_f32_16x16x32_bf16 v[162:165], v[148:151], v[166:169], v[162:165]
	ds_read2_b64 v[166:169], v123 offset0:192 offset1:196
	v_lshlrev_b64 v[178:179], 12, v[174:175]
	v_lshl_add_u64 v[180:181], v[116:117], 0, v[178:179]
	v_mfma_f32_16x16x32_bf16 v[162:165], v[158:161], v[170:173], v[162:165]
	ds_read2_b64 v[170:173], v123 offset0:200 offset1:204
	v_mov_b32_e32 v111, v101
	s_waitcnt lgkmcnt(1)
	v_mfma_f32_16x16x32_bf16 v[52:55], v[52:55], v[166:169], 0
	ds_read2_b64 v[166:169], v123 offset0:208 offset1:212
	ds_read2_b64 v[174:177], v123 offset0:216 offset1:220
	v_mov_b32_e32 v123, v101
	s_waitcnt lgkmcnt(2)
	v_mfma_f32_16x16x32_bf16 v[52:55], v[56:59], v[170:173], v[52:55]
	v_add_u32_e32 v56, s13, v106
	ds_read_b128 v[56:59], v56
	ds_read_b128 v[170:173], v133 offset:36352
	s_waitcnt lgkmcnt(1)
	v_pk_mul_f32 v[58:59], v[86:87], v[58:59]
	v_mfma_f32_16x16x32_bf16 v[52:55], v[148:151], v[166:169], v[52:55]
	ds_read_b128 v[148:151], v133 offset:36416
	ds_read_b128 v[166:169], v135
	global_store_dwordx4 v[180:181], v[144:147], off
	ds_read_b128 v[144:147], v133 offset:38720
	v_mfma_f32_16x16x32_bf16 v[52:55], v[158:161], v[174:177], v[52:55]
	ds_read_b128 v[158:161], v133 offset:38656
	v_pk_mul_f32 v[56:57], v[84:85], v[56:57]
	s_waitcnt lgkmcnt(2)
	v_pk_mul_f32 v[82:83], v[82:83], v[168:169]
	v_pk_mul_f32 v[80:81], v[80:81], v[166:167]
	v_mfma_f32_16x16x32_bf16 v[56:59], v[170:173], v[20:23], v[56:59]
	v_lshl_add_u64 v[170:171], s[16:17], 0, v[178:179]
	s_waitcnt lgkmcnt(0)
	v_mfma_f32_16x16x32_bf16 v[80:83], v[158:161], v[20:23], v[80:83]
	v_mfma_f32_16x16x32_bf16 v[84:87], v[148:151], v[16:19], v[56:59]
	s_nop 3
	ds_read_b128 v[56:59], v136
	ds_read_b128 v[148:151], v133 offset:40960
	ds_read_b128 v[158:161], v133 offset:41024
	ds_read_b128 v[166:169], v137
	s_waitcnt lgkmcnt(3)
	v_pk_mul_f32 v[58:59], v[78:79], v[58:59]
	v_mfma_f32_16x16x32_bf16 v[80:83], v[144:147], v[16:19], v[80:83]
	ds_read_b128 v[144:147], v133 offset:43264
	v_pk_mul_f32 v[56:57], v[76:77], v[56:57]
	s_waitcnt lgkmcnt(3)
	s_nop 0
	v_mfma_f32_16x16x32_bf16 v[56:59], v[148:151], v[20:23], v[56:59]
	ds_read_b128 v[148:151], v133 offset:43328
	s_waitcnt lgkmcnt(3)
	v_mfma_f32_16x16x32_bf16 v[76:79], v[158:161], v[16:19], v[56:59]
	ds_read_b128 v[158:161], v133 offset:45568
	s_waitcnt lgkmcnt(3)
	s_nop 2
	v_pk_mul_f32 v[58:59], v[74:75], v[168:169]
	v_pk_mul_f32 v[56:57], v[72:73], v[166:167]
	ds_read_b128 v[166:169], v133 offset:45632
	s_waitcnt lgkmcnt(3)
	v_mfma_f32_16x16x32_bf16 v[56:59], v[144:147], v[20:23], v[56:59]
	ds_read_b128 v[144:147], v138
	s_waitcnt lgkmcnt(3)
	v_mfma_f32_16x16x32_bf16 v[72:75], v[148:151], v[16:19], v[56:59]
	v_lshl_add_u64 v[148:149], v[170:171], 0, s[24:25]
	v_lshl_add_u64 v[148:149], v[148:149], 0, v[110:111]
	s_nop 2
	ds_read_b128 v[56:59], v139
	s_waitcnt lgkmcnt(1)
	v_pk_mul_f32 v[70:71], v[70:71], v[146:147]
	v_pk_mul_f32 v[68:69], v[68:69], v[144:145]
	ds_read_b128 v[144:147], v133 offset:47872
	s_waitcnt lgkmcnt(1)
	v_pk_mul_f32 v[58:59], v[66:67], v[58:59]
	v_pk_mul_f32 v[56:57], v[64:65], v[56:57]
	ds_read_b128 v[64:67], v133 offset:47936
	v_mfma_f32_16x16x32_bf16 v[68:71], v[158:161], v[20:23], v[68:71]
	v_lshl_add_u64 v[158:159], v[148:149], 0, v[122:123]
	v_add_co_u32_e32 v160, vcc, s31, v158
	s_waitcnt lgkmcnt(1)
	v_mfma_f32_16x16x32_bf16 v[56:59], v[144:147], v[20:23], v[56:59]
	ds_read_b128 v[144:147], v140
	ds_read_b128 v[148:151], v133 offset:50176
	v_addc_co_u32_e32 v161, vcc, 0, v159, vcc
	global_store_dwordx4 v[160:161], v[152:155], off
	s_waitcnt lgkmcnt(1)
	v_pk_mul_f32 v[62:63], v[62:63], v[146:147]
	ds_read_b128 v[152:155], v133 offset:50240
	v_pk_mul_f32 v[60:61], v[60:61], v[144:145]
	ds_read_b128 v[144:147], v133 offset:52480
	v_mfma_f32_16x16x32_bf16 v[64:67], v[64:67], v[16:19], v[56:59]
	s_waitcnt lgkmcnt(2)
	v_mfma_f32_16x16x32_bf16 v[60:63], v[148:151], v[20:23], v[60:63]
	v_add_co_u32_e32 v148, vcc, s33, v158
	ds_read_b128 v[56:59], v141
	s_nop 0
	v_addc_co_u32_e32 v149, vcc, 0, v159, vcc
	global_store_dwordx4 v[148:149], v[162:165], off
	ds_read_b128 v[148:151], v133 offset:52544
	s_waitcnt lgkmcnt(1)
	v_pk_mul_f32 v[50:51], v[50:51], v[58:59]
	v_pk_mul_f32 v[48:49], v[48:49], v[56:57]
	v_add_co_u32_e32 v56, vcc, s34, v158
	s_nop 0
	v_mfma_f32_16x16x32_bf16 v[48:51], v[144:147], v[20:23], v[48:51]
	v_addc_co_u32_e32 v57, vcc, 0, v159, vcc
	global_store_dwordx4 v[56:57], v[52:55], off
	v_mfma_f32_16x16x32_bf16 v[68:71], v[166:169], v[16:19], v[68:71]
	v_mfma_f32_16x16x32_bf16 v[60:63], v[152:155], v[16:19], v[60:63]
	s_waitcnt lgkmcnt(0)
	v_mfma_f32_16x16x32_bf16 v[56:59], v[148:151], v[16:19], v[48:51]
	s_nop 2
	v_mov_b64_e32 v[50:51], v[18:19]
	v_mov_b64_e32 v[48:49], v[16:17]
	s_cbranch_scc1 .LBB0_670
	s_waitcnt vmcnt(14)
	ds_write_b128 v125, v[24:27]
	ds_write_b128 v126, v[28:31] offset:18432
	ds_write_b128 v127, v[32:35]
	ds_write_b128 v128, v[36:39] offset:18432
	s_and_saveexec_b64 s[6:7], s[4:5]
	s_cbranch_execz .LBB0_669
	ds_write_b32 v131, v142 offset:35840
	s_branch .LBB0_669
